# best_v22 + W_in N-tile order rotated by 4*(workgroup%8) per XCD so that different XCDs run different epilogue kinds (z / rotary / gates) at the same time
# speedup vs baseline: 1.0168x; 1.0168x over previous
;     __device__ void init(int M, int N, int G_, int c_) { base.init(M, N, G_, c_); }
;     __device__ bool next(int i, Unit& u) const { Unit t; if (!base.next(i >> 2, t)) return false; const int br = i & 3; u.pm = br * 64 + t.pm; u.pn = br * 4 + t.pn; return true; }
; #define P_IN(i) ((const float*)rd_ptr(i))
;     __host__ __device__ bool next(int i, Unit& u) const {
;         const long L = (long)i * G + c; if (L >= nwg) return false;
;         int wgid = (int)L; { const int q = nwg / NXCD, r = nwg % NXCD, xcd = wgid % NXCD, off = wgid / NXCD; wgid = (xcd < r ? xcd * (q + 1) : r * (q + 1) + (xcd - r) * q) + off; }
;         const int nig = WGM * nN, gid = wgid / nig, fm = gid * WGM, gsz = (nM - fm) < WGM ? (nM - fm) : WGM;
;         u.pm = fm + ((wgid % nig) % gsz); u.pn = (wgid % nig) / gsz; return true;
;     }
; __global__ void __launch_bounds__(NTHR, 2) trunk_fwd(Args args) {
;     ...
;         } else if (kind == 2 && !SK2) {
;             pg8::Gemm g{(const u16*)(ws + WS_XB) + hrow * DM, (const u16*)(wl + WO_IN), MH, 24 * 256, DM}; pg8::StaticOrder S; S.init(MH, 24 * 256, G, bx);
;             pg8::EpiWin E{(u16*)(ws + WS_ZA), (u16*)(ws + WS_QC), (u16*)(ws + WS_KC), (u16*)(ws + WS_VC), (float*)(ws + WS_MIF), (const float*)(ws + WS_SSP) + hrow * 16, (const float*)(ws + WS_COS) + hrow * 32, (const float*)(ws + WS_SIN) + hrow * 32, P_IN(11) + l * 8};
;             pg8::gemm_phase<pg8::EpiWin, pg8::StaticOrder, PG8_ALIGN, PG8_SP2>(lds, g, S, E);
.LBB0_1116:
	s_andn2_b64 vcc, exec, s[0:1]
	s_cbranch_vccnz .LBB0_1363
	s_cmp_lt_i32 s79, 1
	s_mov_b64 s[0:1], -1
	s_cbranch_scc1 .LBB0_1346
	s_cmp_gt_i32 s79, 1
	s_cbranch_scc0 .LBB0_1298
	v_mov_b32_e32 v0, 0x21058
	ds_read_b64 v[0:1], v0
	s_cmpk_lt_i32 s58, 0x600
	s_cselect_b64 s[0:1], -1, 0
	s_cmpk_gt_i32 s58, 0x5ff
	s_waitcnt lgkmcnt(0)
	v_readfirstlane_b32 s22, v0
	v_mov_b32_e32 v0, v230
	v_readfirstlane_b32 s3, v1
	s_nop 0
	v_readfirstlane_b32 s2, v0
	s_cbranch_scc1 .LBB0_1121
	s_ashr_i32 s4, s58, 31
	s_lshr_b32 s4, s4, 29
	s_add_i32 s4, s58, s4
	s_ashr_i32 s5, s4, 3
	s_and_b32 s4, s4, -8
	s_sub_i32 s4, s58, s4
	s_cmp_lt_i32 s4, 0
	s_movk_i32 s6, 0xc1
	s_cselect_b32 s6, s6, 0xc0
	s_mul_i32 s4, s4, s6
	s_add_i32 s4, s4, s5
	s_mul_hi_i32 s5, s4, 0x2aaaaaab
	s_lshr_b32 s6, s5, 31
	s_ashr_i32 s5, s5, 5
	s_add_i32 s5, s5, s6
	s_lshl_b32 s6, s5, 3
	s_mulk_i32 s5, 0xc0
	s_sub_i32 s4, s4, s5
	s_bfe_u32 s5, s4, 0x3001c
	s_add_i32 s5, s4, s5
	s_sext_i32_i16 s7, s5
	s_and_b32 s5, s5, 0xfff8
	s_sub_i32 s4, s4, s5
	s_sext_i32_i16 s4, s4
	s_add_i32 s4, s6, s4
	s_ashr_i32 s8, s7, 3
	v_readlane_b32 s5, v255, 2
	s_and_b32 s5, s5, 7
	s_lshl_b32 s5, s5, 2
	s_add_i32 s8, s8, s5
	s_cmp_ge_u32 s8, 24
	s_cselect_b32 s5, 24, 0
	s_sub_i32 s8, s8, s5
	s_cmp_ge_u32 s8, 24
	s_cselect_b32 s5, 24, 0
	s_sub_i32 s8, s8, s5

;     __device__ bool next(int i, Unit& u) const { Unit t; if (!base.next(i >> 2, t)) return false; const int br = i & 3; u.pm = br * 64 + t.pm; u.pn = br * 4 + t.pn; return true; }
;     __host__ __device__ bool next(int i, Unit& u) const {
;         const long L = (long)i * G + c; if (L >= nwg) return false;
;         int wgid = (int)L; { const int q = nwg / NXCD, r = nwg % NXCD, xcd = wgid % NXCD, off = wgid / NXCD; wgid = (xcd < r ? xcd * (q + 1) : r * (q + 1) + (xcd - r) * q) + off; }
;         const int nig = WGM * nN, gid = wgid / nig, fm = gid * WGM, gsz = (nM - fm) < WGM ? (nM - fm) : WGM;
;         u.pm = fm + ((wgid % nig) % gsz); u.pn = (wgid % nig) / gsz; return true;
;     }
; template <class Epi, class Sched, bool ALIGN_EPI = false, bool SP2 = false>
; __device__ __forceinline__ void gemm_phase(PG8_LAS unsigned char* lds, const Gemm g, const Sched& S, const Epi& E) {
;     ...
;         const bool has_next = S.next(ui + 1, nxt);
;         const char* nA = has_next ? (const char*)g.A + (size_t)nxt.pm * tstep : cA; const char* nB = has_next ? (const char*)g.Bt + (size_t)nxt.pn * tstep : cB;
.LBB0_1127:
	s_add_i32 s1, s1, 1
	s_mul_i32 s2, s1, s39
	s_mul_hi_u32 s3, s1, s60
	s_add_i32 s3, s3, s2
	s_mul_i32 s2, s1, s60
	s_add_u32 s80, s2, s58
	s_addc_u32 s81, s3, s50
	v_mov_b64_e32 v[0:1], 0x600
	v_cmp_lt_i64_e64 s[2:3], s[80:81], v[0:1]
	v_mov_b64_e32 v[0:1], 0x5ff
	v_cmp_gt_i64_e32 vcc, s[80:81], v[0:1]
	s_cbranch_vccnz .LBB0_1129
	s_ashr_i32 s5, s80, 31
	s_lshr_b32 s5, s5, 29
	s_add_i32 s5, s80, s5
	s_ashr_i32 s9, s5, 3
	s_and_b32 s5, s5, -8
	s_sub_i32 s5, s80, s5
	s_cmp_lt_i32 s5, 0
	s_movk_i32 s22, 0xc1
	s_cselect_b32 s22, s22, 0xc0
	s_mul_i32 s5, s5, s22
	s_add_i32 s5, s5, s9
	s_mul_hi_i32 s9, s5, 0x2aaaaaab
	s_lshr_b32 s22, s9, 31
	s_ashr_i32 s9, s9, 5
	s_add_i32 s9, s9, s22
	s_lshl_b32 s22, s9, 3
	s_sub_i32 s23, 64, s22
	s_min_i32 s23, s23, 8
	s_abs_i32 s30, s23
	v_cvt_f32_u32_e32 v0, s30
	s_sub_i32 s40, 0, s30
	s_mulk_i32 s9, 0xc0
	s_sub_i32 s5, s5, s9
	v_rcp_iflag_f32_e32 v0, v0
	s_abs_i32 s9, s5
	s_xor_b32 s37, s5, s23
	s_ashr_i32 s37, s37, 31
	v_mul_f32_e32 v0, 0x4f7ffffe, v0
	v_cvt_u32_f32_e32 v0, v0
	s_nop 0
	v_readfirstlane_b32 s76, v0
	s_mul_i32 s40, s40, s76
	s_mul_hi_u32 s40, s76, s40
	s_add_i32 s76, s76, s40
	s_mul_hi_u32 s40, s9, s76
	s_mul_i32 s76, s40, s30
	s_sub_i32 s9, s9, s76
	s_add_i32 s77, s40, 1
	s_sub_i32 s76, s9, s30
	s_cmp_ge_u32 s9, s30
	s_cselect_b32 s40, s77, s40
	s_cselect_b32 s9, s76, s9
	s_add_i32 s76, s40, 1
	s_cmp_ge_u32 s9, s30
	s_cselect_b32 s9, s76, s40
	s_xor_b32 s9, s9, s37
	s_sub_i32 s76, s9, s37
	s_mul_i32 s9, s76, s23
	s_sub_i32 s5, s5, s9
	s_add_i32 s78, s22, s5
	v_readlane_b32 s77, v255, 2
	s_and_b32 s77, s77, 7
	s_lshl_b32 s77, s77, 2
	s_add_i32 s76, s76, s77
	s_cmp_ge_u32 s76, 24
	s_cselect_b32 s77, 24, 0
	s_sub_i32 s76, s76, s77
	s_cmp_ge_u32 s76, 24
	s_cselect_b32 s77, 24, 0
	s_sub_i32 s76, s76, s77
